# h1 RMSNorm work queue (after the first residual GEMM) also takes the most recently written 2048-row chunks first
# baseline (speedup 1.0000x reference)
; #define INP(i) ((const float*)tab_get(lds, (i)))
; #define OUTP() ((float*)tab_get(lds, 30))
; #define WSB(off) ((bf16*)((unsigned char*)tab_get(lds, 31) + (off)))
; #define fresh_lane() (my_tid(lds) & 63)
; #define QNEXT(ctrw, dst) do { __syncthreads(); if (my_tid(lds) == 0) *(volatile LAS int*)(lds + TAB_OFF + 264) = (int)atomicAdd((unsigned*)tab_get(lds, 31) + 8192 + 64 * (ctrw), 1u); \
;         __syncthreads(); dst = __builtin_amdgcn_readfirstlane(*(volatile LAS int*)(lds + TAB_OFF + 264)); } while (0)
; __global__ void __launch_bounds__(512, 2) mega_fwd(Params p) {
;     ...
;         { const int lane = fresh_lane(); const float* X = OUTP(); const float* g = INP(18); bf16* H = WSB(WS_H);
;           for (;;) { int it; QNEXT(1, it); if (it >= MP / 64) break;
; #pragma unroll 1
;               for (int k = 0; k < 8; k += 2) { const int m = it * 64 + wave * 8 + k; rms_row2_to_bf16(X + (size_t)m * DM, X + (size_t)(m + 1) * DM, g, H + (size_t)m * DM, H + (size_t)(m + 1) * DM, lane); } } }
.LBB0_1065:
	s_or_b64 exec, exec, s[2:3]
	s_waitcnt lgkmcnt(0)
	s_barrier
	ds_read_b32 v0, v25
	s_mov_b64 s[2:3], -1
	s_waitcnt lgkmcnt(0)
	v_readfirstlane_b32 s1, v0
	s_cmpk_gt_i32 s1, 0x1ff
	s_cbranch_scc1 .LBB0_1062
	s_lshr_b32 s2, s1, 5
	s_and_b32 s3, s1, 31
	s_lshl_b32 s1, s2, 1
	s_or_b32 s1, s1, 1
	s_cmp_lt_u32 s2, 8
	s_cselect_b32 s2, 0, 17
	s_sub_i32 s1, s1, s2
	s_lshl_b32 s1, s1, 5
	s_or_b32 s1, s1, s3
	s_lshl_b32 s1, s1, 6
	s_add_i32 s2, s1, s70
	s_ashr_i32 s3, s2, 31
	s_lshl_b64 s[10:11], s[2:3], 11
	s_lshl_b64 s[2:3], s[2:3], 12
	v_lshl_add_u64 v[20:21], v[14:15], 0, s[10:11]
	v_lshl_add_u64 v[22:23], v[16:17], 0, s[2:3]
	s_mov_b32 s1, -2
